# attn1 step loop: LDS-write waits count only the older tile's loads (vmcnt 3/2 when the next tile's loads were just issued, else 1/0), doubling the K/V prefetch distance
# baseline (speedup 1.0000x reference)
;     ...
;         auto gload = [&](u32x4 (&rg)[NJ], float& ckr, int t) {
; #pragma unroll
;             for (int j = 0; j < NJ; ++j) rg[j] = *(const u32x4*)(src[j] + (size_t)t * step[j]);
;             if (MODE == 1 && tid < 64) ckr = ckp[t * 64 + tid];
;         };
;         auto lstore = [&](const u32x4 (&rg)[NJ], const float ckr, int stg) {
;             unsigned char* sb = lds + stg * STG;
; #pragma unroll
;             for (int j = 0; j < NJ; ++j) {
;                 if (j < NKJ) *(u32x4*)(sb + j * 9216 + lrow * 144 + lkc * 16) = rg[j];
;                 else { unsigned char* d = sb + VT_OFF + (lrow + 64 * (j - NKJ)) * 136 + lkc * 16; u32x2 a, c; a.x = rg[j].x; a.y = rg[j].y; c.x = rg[j].z; c.y = rg[j].w; *(u32x2*)d = a; *(u32x2*)(d + 8) = c; }
;             }
;             if (MODE == 1 && tid < 64) *(float*)(sb + CK_OFF + tid * 4) = ckr;
;         };
;     ...
;         auto stepf = [&](f32x16 (&s_cur)[2], const float mi_cur, f32x16 (&s_nxt)[2], float& mi_nxt, u32x4 (&rg_ld)[NJ], float& ck_ld, const u32x4 (&rg_st)[NJ], const float ck_st, int kk) {
;             const int kt = j0 + kk;
;             if (DEEP) { if (kk + 3 < ntl) gload(rg_ld, ck_ld, kt + 3); } else { if (kk + 2 < ntl) gload(rg_ld, ck_ld, kt + 2); }
;             if (MODE == 2 && kk + 2 < ntl) wnext2 = mrow[kt + 2];
;             if (kk + 1 < ntl && (kt + 1) * 64 <= qw0 + 31) qk(s_nxt, mi_nxt, (kk + 1) % 3);
;             if (kt * 64 <= qw0 + 31) softmax_pv(s_cur, mi_cur, kt, kk % 3);
;             if (MODE == 2) { wcur = wnext; wnext = wnext2; }
;             if (kk + 2 < ntl) lstore(rg_st, ck_st, (kk + 2) % 3);
;             __syncthreads();
.LBB0_1367:
	s_or_b64 exec, exec, s[28:29]
	s_mul_hi_u32 s0, s52, 0xaaaaaaab
	s_lshr_b32 s0, s0, 1
	s_add_i32 s58, s51, -2
	s_cmp_ge_i32 s58, s19
	s_mul_i32 s0, s0, 0xd800
	s_cbranch_scc1 .LBB0_1371
	v_subrev_u32_e32 v2, s0, v213
	v_subrev_u32_e32 v4, s0, v177
	v_add_u32_e32 v5, s50, v214
	v_add_u32_e32 v4, v5, v4
	v_add3_u32 v2, v5, v2, s45
	s_add_i32 s1, s51, -1
	s_cmp_lt_i32 s1, s19
	s_cbranch_scc0 .Lva1_t
	s_waitcnt vmcnt(3)
	ds_write_b128 v4, v[118:121]
	s_waitcnt vmcnt(2)
	ds_write2_b64 v2, v[122:123], v[124:125] offset1:1
	s_branch .Lva1_j
.Lva1_t:
	s_waitcnt vmcnt(1)
	ds_write_b128 v4, v[118:121]
	s_waitcnt vmcnt(0)
	ds_write2_b64 v2, v[122:123], v[124:125] offset1:1
.Lva1_j:
	s_and_saveexec_b64 s[8:9], s[2:3]
	v_subrev_u32_e32 v2, s0, v176
	s_add_i32 s1, s50, 0
	v_add_u32_e32 v2, s1, v2
	ds_write_b32 v2, v157
	s_or_b64 exec, exec, s[8:9]

;     ...
;         auto lstore = [&](const u32x4 (&rg)[NJ], const float ckr, int stg) {
;             unsigned char* sb = lds + stg * STG;
; #pragma unroll
;             for (int j = 0; j < NJ; ++j) {
;                 if (j < NKJ) *(u32x4*)(sb + j * 9216 + lrow * 144 + lkc * 16) = rg[j];
;                 else { unsigned char* d = sb + VT_OFF + (lrow + 64 * (j - NKJ)) * 136 + lkc * 16; u32x2 a, c; a.x = rg[j].x; a.y = rg[j].y; c.x = rg[j].z; c.y = rg[j].w; *(u32x2*)d = a; *(u32x2*)(d + 8) = c; }
;             }
;             if (MODE == 1 && tid < 64) *(float*)(sb + CK_OFF + tid * 4) = ckr;
;         };
;     ...
;             if (kk + 2 < ntl) lstore(rg_st, ck_st, (kk + 2) % 3);
.LBB0_1388:
	s_mul_hi_u32 s0, s54, 0xaaaaaaab
	s_lshr_b32 s0, s0, 1
	s_mul_i32 s0, s0, 0xd800
	v_subrev_u32_e32 v2, s0, v213
	v_subrev_u32_e32 v4, s0, v181
	v_add_u32_e32 v5, s50, v214
	v_add_u32_e32 v4, v5, v4
	v_add3_u32 v2, v5, v2, s46
	s_cmp_lt_i32 s51, s19
	s_cbranch_scc0 .Lva2_t
	s_waitcnt vmcnt(3)
	ds_write_b128 v4, v[142:145]
	s_waitcnt vmcnt(2)
	ds_write2_b64 v2, v[146:147], v[148:149] offset1:1
	s_branch .Lva2_j
.Lva2_t:
	s_waitcnt vmcnt(1)
	ds_write_b128 v4, v[142:145]
	s_waitcnt vmcnt(0)
	ds_write2_b64 v2, v[146:147], v[148:149] offset1:1
.Lva2_j:
	s_and_saveexec_b64 s[6:7], s[2:3]
	s_cbranch_execz .LBB0_1349
	v_subrev_u32_e32 v2, s0, v180
	s_add_i32 s0, s50, 0
	v_add_u32_e32 v2, s0, v2
	ds_write_b32 v2, v151
	s_branch .LBB0_1349
